# attention items dequeued dynamically: per-batch ticket counters keyed by XCC id, big-first order, next ticket drawn in the item's last step and broadcast through LDS
# speedup vs baseline: 1.0641x; 1.0062x over previous
.LBB0_469:
	s_or_b64 exec, exec, s[6:7]
	s_add_u32 s4, s38, 0x6000000
	s_addc_u32 s5, s39, 0
	s_mov_b32 s43, 0
	s_add_u32 s40, s38, 0x6500000
	s_mov_b32 s3, s43
	s_addc_u32 s41, s39, 0
	s_lshl_b64 s[6:7], s[2:3], 3
	s_add_u32 s3, s0, s6
	s_addc_u32 s67, s1, s7
	s_cmpk_lg_i32 s33, 0x100
	s_cselect_b64 s[44:45], -1, 0
	s_add_u32 s46, s38, 0x2080000
	s_addc_u32 s47, s39, 0
	s_add_u32 s48, s38, 0x57c0000
	s_addc_u32 s49, s39, 0
	s_add_u32 s50, s38, 0x67a8000
	s_addc_u32 s51, s39, 0
	s_add_u32 s52, s38, 0x77e8000
	s_movk_i32 s68, 0x100
	s_addc_u32 s53, s39, 0
	v_mov_b32_e32 v1, 0
	s_movk_i32 s69, 0xa00
	s_movk_i32 s70, 0xa0
	s_movk_i32 s71, 0x140
	s_mov_b64 s[54:55], 0x2800
	s_movk_i32 s72, 0x2000
	s_mov_b64 s[56:57], 0x100
	s_movk_i32 s73, 0x800
	s_mov_b64 s[58:59], 0x5100
	s_mov_b64 s[60:61], 0x5000
	s_movk_i32 s74, 0x1000
	s_movk_i32 s75, 0x3000
	v_mov_b32_e32 v164, 0xf149f2ca
	v_mbcnt_hi_u32_b32 v197, -1, v214
	s_mov_b32 s42, s43
	s_bfe_u32 s10, s83, 0x10001
	s_lshl_b32 s10, s10, 8
	s_addk_i32 s10, 0x3700
	s_and_saveexec_b64 s[6:7], s[80:81]
	s_cbranch_execz .Lq_init_done
	v_mov_b32_e32 v2, s10
	v_mov_b32_e32 v3, 1
	global_atomic_add v215, v2, v3, s[78:79] sc0
	s_waitcnt vmcnt(0)
	v_mov_b32_e32 v2, 0xf000
	ds_write_b32 v2, v215
	s_waitcnt lgkmcnt(0)
.Lq_init_done:
	s_or_b64 exec, exec, s[6:7]
	s_barrier
	s_branch .LBB0_472
.LBB0_470:
	s_or_b64 exec, exec, s[6:7]
	s_and_saveexec_b64 s[6:7], s[80:81]
	s_cbranch_execz .Lq_pub_done
	v_mov_b32_e32 v2, 0xf000
	ds_write_b32 v2, v215
	s_waitcnt lgkmcnt(0)

.LBB0_474:
	s_andn2_b64 vcc, exec, s[8:9]
	s_cbranch_vccnz .LBB0_477
	s_barrier
	v_mov_b32_e32 v0, 0xf000
	ds_read_b32 v0, v0
	s_waitcnt lgkmcnt(0)
	v_readfirstlane_b32 s14, v0
	s_bfe_u32 s11, s83, 0x10001
	s_cmpk_lt_u32 s14, 0x104
	s_cselect_b64 s[6:7], -1, 0
	s_cmpk_lt_u32 s14, 0xde
	s_cbranch_scc1 .Lq_prompt
	s_cmpk_lt_u32 s14, 0xe2
	s_cbranch_scc0 .Lq_late
	s_lshl_b32 s10, s11, 2
	s_add_i32 s14, s14, s10
	s_addk_i32 s14, 0x122
	s_branch .Lq_done
.Lq_late:
	s_add_i32 s14, s14, -4
.Lq_prompt:
	s_lshr_b32 s10, s14, 1
	s_sub_u32 s10, 0x7f, s10
	s_lshl_b32 s10, s10, 1
	s_and_b32 s14, s14, 1
	s_or_b32 s14, s14, s10
	s_lshl_b32 s11, s11, 8
	s_or_b32 s14, s14, s11
.Lq_done:



.Lat3_tail_a:
	ds_read_b64_tr_b16 v[204:205], v155 offset:8192
	ds_read_b64_tr_b16 v[206:207], v171 offset:8192
	ds_read_b64_tr_b16 v[208:209], v168 offset:8192
	ds_read_b64_tr_b16 v[210:211], v172 offset:8192
	ds_read_b64_tr_b16 v[176:177], v169 offset:8192
	ds_read_b64_tr_b16 v[178:179], v173 offset:8192
	ds_read_b64_tr_b16 v[184:185], v170 offset:8192
	ds_read_b64_tr_b16 v[186:187], v174 offset:8192
	s_bfe_u32 s10, s83, 0x10001
	s_lshl_b32 s10, s10, 8
	s_addk_i32 s10, 0x3700
	s_and_saveexec_b64 s[18:19], s[80:81]
	s_cbranch_execz .Lat3_tk_ta
	v_mov_b32_e32 v2, s10
	v_mov_b32_e32 v3, 1
	global_atomic_add v215, v2, v3, s[78:79] sc0
.Lat3_tk_ta:
	s_or_b64 exec, exec, s[18:19]
	v_and_b32_e32 v3, 63, v165
	v_lshlrev_b32_e32 v3, 4, v3
	v_lshl_add_u32 v3, v154, 14, v3
	v_add_u32_e32 v4, 0x1000, v3
	v_add_u32_e32 v5, 0x2000, v3
	v_add_u32_e32 v213, 0x3000, v3
	global_load_dwordx4 v[148:151], v3, s[48:49] offset:0
	global_load_dwordx4 v[144:147], v5, s[48:49] offset:0
	global_load_dwordx4 v[140:143], v3, s[48:49] offset:1024
	global_load_dwordx4 v[136:139], v5, s[48:49] offset:1024
	global_load_dwordx4 v[132:135], v3, s[48:49] offset:2048
	global_load_dwordx4 v[128:131], v5, s[48:49] offset:2048
	global_load_dwordx4 v[124:127], v3, s[48:49] offset:3072
	global_load_dwordx4 v[120:123], v5, s[48:49] offset:3072
	global_load_dwordx4 v[116:119], v4, s[48:49] offset:0
	global_load_dwordx4 v[112:115], v213, s[48:49] offset:0
	global_load_dwordx4 v[220:223], v4, s[48:49] offset:1024
	global_load_dwordx4 v[224:227], v213, s[48:49] offset:1024
	global_load_dwordx4 v[228:231], v4, s[48:49] offset:2048
	global_load_dwordx4 v[96:99], v213, s[48:49] offset:2048
	global_load_dwordx4 v[100:103], v4, s[48:49] offset:3072
	global_load_dwordx4 v[104:107], v213, s[48:49] offset:3072
	v_and_b32_e32 v212, 0xffffffc0, v165
	v_lshlrev_b32_e32 v212, 1, v212
	v_lshl_add_u32 v212, v152, 10, v212
	v_lshl_add_u32 v212, v166, 1, v212
	global_load_dwordx2 v[190:191], v212, s[50:51] offset:0
	global_load_dwordx2 v[192:193], v212, s[50:51] offset:16
	global_load_dwordx2 v[194:195], v212, s[50:51] offset:32
	global_load_dwordx2 v[198:199], v212, s[50:51] offset:48
	global_load_dwordx2 v[200:201], v212, s[50:51] offset:64
	global_load_dwordx2 v[202:203], v212, s[50:51] offset:80
	global_load_dwordx2 v[216:217], v212, s[50:51] offset:96
	global_load_dwordx2 v[248:249], v212, s[50:51] offset:112
	v_exp_f32_e32 v80, v80
	v_exp_f32_e32 v81, v81
	v_exp_f32_e32 v82, v82
	v_exp_f32_e32 v83, v83
	v_exp_f32_e32 v84, v84
	v_exp_f32_e32 v85, v85
	v_cvt_pk_bf16_f32 v6, v80, v81
	v_exp_f32_e32 v86, v86
	v_exp_f32_e32 v87, v87
	v_cvt_pk_bf16_f32 v7, v82, v83
	v_cvt_pk_bf16_f32 v8, v84, v85
	v_exp_f32_e32 v88, v88
	v_exp_f32_e32 v89, v89
	v_cvt_pk_bf16_f32 v9, v86, v87
	s_nop 1
	s_waitcnt lgkmcnt(6)
	v_mfma_f32_32x32x16_bf16 v[64:79], v[204:207], v[6:9], v[64:79]
	ds_read_b64_tr_b16 v[204:205], v155 offset:12288
	ds_read_b64_tr_b16 v[206:207], v171 offset:12288
	v_exp_f32_e32 v90, v90
	v_exp_f32_e32 v91, v91
	v_cvt_pk_bf16_f32 v10, v88, v89
	s_waitcnt lgkmcnt(6)
	v_mfma_f32_32x32x16_bf16 v[48:63], v[208:211], v[6:9], v[48:63]
	ds_read_b64_tr_b16 v[208:209], v168 offset:12288
	ds_read_b64_tr_b16 v[210:211], v172 offset:12288
	v_exp_f32_e32 v92, v92
	v_exp_f32_e32 v93, v93
	v_cvt_pk_bf16_f32 v11, v90, v91
	s_waitcnt lgkmcnt(6)
	v_mfma_f32_32x32x16_bf16 v[32:47], v[176:179], v[6:9], v[32:47]
	ds_read_b64_tr_b16 v[176:177], v169 offset:12288
	ds_read_b64_tr_b16 v[178:179], v173 offset:12288
	v_exp_f32_e32 v94, v94
	v_exp_f32_e32 v95, v95
	s_waitcnt lgkmcnt(6)
	v_mfma_f32_32x32x16_bf16 v[16:31], v[184:187], v[6:9], v[16:31]
	ds_read_b64_tr_b16 v[184:185], v170 offset:12288
	ds_read_b64_tr_b16 v[186:187], v174 offset:12288
	v_cvt_pk_bf16_f32 v12, v92, v93
	v_cvt_pk_bf16_f32 v13, v94, v95
	s_nop 1
	s_waitcnt lgkmcnt(6)
	v_mfma_f32_32x32x16_bf16 v[64:79], v[204:207], v[10:13], v[64:79]
	v_add_f32_e32 v175, v175, v80
	v_add_f32_e32 v175, v175, v81
	v_add_f32_e32 v175, v175, v82
	v_add_f32_e32 v175, v175, v83
	s_waitcnt lgkmcnt(4)
	v_mfma_f32_32x32x16_bf16 v[48:63], v[208:211], v[10:13], v[48:63]
	v_add_f32_e32 v175, v175, v84
	v_add_f32_e32 v175, v175, v85
	v_add_f32_e32 v175, v175, v86
	v_add_f32_e32 v175, v175, v87
	s_waitcnt lgkmcnt(2)
	v_mfma_f32_32x32x16_bf16 v[32:47], v[176:179], v[10:13], v[32:47]
	v_add_f32_e32 v175, v175, v88
	v_add_f32_e32 v175, v175, v89
	v_add_f32_e32 v175, v175, v90
	v_add_f32_e32 v175, v175, v91
	s_waitcnt lgkmcnt(0)
	v_mfma_f32_32x32x16_bf16 v[16:31], v[184:187], v[10:13], v[16:31]
	v_add_f32_e32 v175, v175, v92
	v_add_f32_e32 v175, v175, v93
	v_add_f32_e32 v175, v175, v94
	v_add_f32_e32 v175, v175, v95
	s_branch .Lat3_epi_b
.Lat3_tail_b:
	ds_read_b64_tr_b16 v[204:205], v155 offset:28672
	ds_read_b64_tr_b16 v[206:207], v171 offset:28672
	ds_read_b64_tr_b16 v[208:209], v168 offset:28672
	ds_read_b64_tr_b16 v[210:211], v172 offset:28672
	ds_read_b64_tr_b16 v[176:177], v169 offset:28672
	ds_read_b64_tr_b16 v[178:179], v173 offset:28672
	ds_read_b64_tr_b16 v[184:185], v170 offset:28672
	ds_read_b64_tr_b16 v[186:187], v174 offset:28672
	s_bfe_u32 s10, s83, 0x10001
	s_lshl_b32 s10, s10, 8
	s_addk_i32 s10, 0x3700
	s_and_saveexec_b64 s[18:19], s[80:81]
	s_cbranch_execz .Lat3_tk_tb
	v_mov_b32_e32 v2, s10
	v_mov_b32_e32 v3, 1
	global_atomic_add v215, v2, v3, s[78:79] sc0
.Lat3_tk_tb:
	s_or_b64 exec, exec, s[18:19]
	v_and_b32_e32 v3, 63, v165
	v_lshlrev_b32_e32 v3, 4, v3
	v_lshl_add_u32 v3, v154, 14, v3
	v_add_u32_e32 v4, 0x1000, v3
	v_add_u32_e32 v5, 0x2000, v3
	v_add_u32_e32 v213, 0x3000, v3
	global_load_dwordx4 v[148:151], v3, s[48:49] offset:0
	global_load_dwordx4 v[144:147], v5, s[48:49] offset:0
	global_load_dwordx4 v[140:143], v3, s[48:49] offset:1024
	global_load_dwordx4 v[136:139], v5, s[48:49] offset:1024
	global_load_dwordx4 v[132:135], v3, s[48:49] offset:2048
	global_load_dwordx4 v[128:131], v5, s[48:49] offset:2048
	global_load_dwordx4 v[124:127], v3, s[48:49] offset:3072
	global_load_dwordx4 v[120:123], v5, s[48:49] offset:3072
	global_load_dwordx4 v[116:119], v4, s[48:49] offset:0
	global_load_dwordx4 v[112:115], v213, s[48:49] offset:0
	global_load_dwordx4 v[220:223], v4, s[48:49] offset:1024
	global_load_dwordx4 v[224:227], v213, s[48:49] offset:1024
	global_load_dwordx4 v[228:231], v4, s[48:49] offset:2048
	global_load_dwordx4 v[96:99], v213, s[48:49] offset:2048
	global_load_dwordx4 v[100:103], v4, s[48:49] offset:3072
	global_load_dwordx4 v[104:107], v213, s[48:49] offset:3072
	v_and_b32_e32 v212, 0xffffffc0, v165
	v_lshlrev_b32_e32 v212, 1, v212
	v_lshl_add_u32 v212, v152, 10, v212
	v_lshl_add_u32 v212, v166, 1, v212
	global_load_dwordx2 v[190:191], v212, s[50:51] offset:0
	global_load_dwordx2 v[192:193], v212, s[50:51] offset:16
	global_load_dwordx2 v[194:195], v212, s[50:51] offset:32
	global_load_dwordx2 v[198:199], v212, s[50:51] offset:48
	global_load_dwordx2 v[200:201], v212, s[50:51] offset:64
	global_load_dwordx2 v[202:203], v212, s[50:51] offset:80
	global_load_dwordx2 v[216:217], v212, s[50:51] offset:96
	global_load_dwordx2 v[248:249], v212, s[50:51] offset:112
	v_exp_f32_e32 v80, v80
	v_exp_f32_e32 v81, v81
	v_exp_f32_e32 v82, v82
	v_exp_f32_e32 v83, v83
	v_exp_f32_e32 v84, v84
	v_exp_f32_e32 v85, v85
	v_cvt_pk_bf16_f32 v6, v80, v81
	v_exp_f32_e32 v86, v86
	v_exp_f32_e32 v87, v87
	v_cvt_pk_bf16_f32 v7, v82, v83
	v_cvt_pk_bf16_f32 v8, v84, v85
	v_exp_f32_e32 v88, v88
	v_exp_f32_e32 v89, v89
	v_cvt_pk_bf16_f32 v9, v86, v87
	s_nop 1
	s_waitcnt lgkmcnt(6)
	v_mfma_f32_32x32x16_bf16 v[64:79], v[204:207], v[6:9], v[64:79]
	ds_read_b64_tr_b16 v[204:205], v155 offset:32768
	ds_read_b64_tr_b16 v[206:207], v171 offset:32768
	v_exp_f32_e32 v90, v90
	v_exp_f32_e32 v91, v91
	v_cvt_pk_bf16_f32 v10, v88, v89
	s_waitcnt lgkmcnt(6)
	v_mfma_f32_32x32x16_bf16 v[48:63], v[208:211], v[6:9], v[48:63]
	ds_read_b64_tr_b16 v[208:209], v168 offset:32768
	ds_read_b64_tr_b16 v[210:211], v172 offset:32768
	v_exp_f32_e32 v92, v92
	v_exp_f32_e32 v93, v93
	v_cvt_pk_bf16_f32 v11, v90, v91
	s_waitcnt lgkmcnt(6)
	v_mfma_f32_32x32x16_bf16 v[32:47], v[176:179], v[6:9], v[32:47]
	ds_read_b64_tr_b16 v[176:177], v169 offset:32768
	ds_read_b64_tr_b16 v[178:179], v173 offset:32768
	v_exp_f32_e32 v94, v94
	v_exp_f32_e32 v95, v95
	s_waitcnt lgkmcnt(6)
	v_mfma_f32_32x32x16_bf16 v[16:31], v[184:187], v[6:9], v[16:31]
	ds_read_b64_tr_b16 v[184:185], v170 offset:32768
	ds_read_b64_tr_b16 v[186:187], v174 offset:32768
	v_cvt_pk_bf16_f32 v12, v92, v93
	v_cvt_pk_bf16_f32 v13, v94, v95
	s_nop 1
	s_waitcnt lgkmcnt(6)
	v_mfma_f32_32x32x16_bf16 v[64:79], v[204:207], v[10:13], v[64:79]
	v_add_f32_e32 v175, v175, v80
	v_add_f32_e32 v175, v175, v81
	v_add_f32_e32 v175, v175, v82
	v_add_f32_e32 v175, v175, v83
	s_waitcnt lgkmcnt(4)
	v_mfma_f32_32x32x16_bf16 v[48:63], v[208:211], v[10:13], v[48:63]
	v_add_f32_e32 v175, v175, v84
	v_add_f32_e32 v175, v175, v85
	v_add_f32_e32 v175, v175, v86
	v_add_f32_e32 v175, v175, v87
	s_waitcnt lgkmcnt(2)
	v_mfma_f32_32x32x16_bf16 v[32:47], v[176:179], v[10:13], v[32:47]
	v_add_f32_e32 v175, v175, v88
	v_add_f32_e32 v175, v175, v89
	v_add_f32_e32 v175, v175, v90
	v_add_f32_e32 v175, v175, v91
	s_waitcnt lgkmcnt(0)
	v_mfma_f32_32x32x16_bf16 v[16:31], v[184:187], v[10:13], v[16:31]
	v_add_f32_e32 v175, v175, v92
	v_add_f32_e32 v175, v175, v93
	v_add_f32_e32 v175, v175, v94
	v_add_f32_e32 v175, v175, v95
	s_branch .Lat3_epi_b
.Lat3_tail_c:
	ds_read_b64_tr_b16 v[204:205], v155 offset:49152
	ds_read_b64_tr_b16 v[206:207], v171 offset:49152
	ds_read_b64_tr_b16 v[208:209], v168 offset:49152
	ds_read_b64_tr_b16 v[210:211], v172 offset:49152
	ds_read_b64_tr_b16 v[176:177], v169 offset:49152
	ds_read_b64_tr_b16 v[178:179], v173 offset:49152
	ds_read_b64_tr_b16 v[184:185], v170 offset:49152
	ds_read_b64_tr_b16 v[186:187], v174 offset:49152
	s_bfe_u32 s10, s83, 0x10001
	s_lshl_b32 s10, s10, 8
	s_addk_i32 s10, 0x3700
	s_and_saveexec_b64 s[18:19], s[80:81]
	s_cbranch_execz .Lat3_tk_tc
	v_mov_b32_e32 v2, s10
	v_mov_b32_e32 v3, 1
	global_atomic_add v215, v2, v3, s[78:79] sc0
.Lat3_tk_tc:
	s_or_b64 exec, exec, s[18:19]
	v_and_b32_e32 v3, 63, v165
	v_lshlrev_b32_e32 v3, 4, v3
	v_lshl_add_u32 v3, v154, 14, v3
	v_add_u32_e32 v4, 0x1000, v3
	v_add_u32_e32 v5, 0x2000, v3
	v_add_u32_e32 v213, 0x3000, v3
	global_load_dwordx4 v[148:151], v3, s[48:49] offset:0
	global_load_dwordx4 v[144:147], v5, s[48:49] offset:0
	global_load_dwordx4 v[140:143], v3, s[48:49] offset:1024
	global_load_dwordx4 v[136:139], v5, s[48:49] offset:1024
	global_load_dwordx4 v[132:135], v3, s[48:49] offset:2048
	global_load_dwordx4 v[128:131], v5, s[48:49] offset:2048
	global_load_dwordx4 v[124:127], v3, s[48:49] offset:3072
	global_load_dwordx4 v[120:123], v5, s[48:49] offset:3072
	global_load_dwordx4 v[116:119], v4, s[48:49] offset:0
	global_load_dwordx4 v[112:115], v213, s[48:49] offset:0
	global_load_dwordx4 v[220:223], v4, s[48:49] offset:1024
	global_load_dwordx4 v[224:227], v213, s[48:49] offset:1024
	global_load_dwordx4 v[228:231], v4, s[48:49] offset:2048
	global_load_dwordx4 v[96:99], v213, s[48:49] offset:2048
	global_load_dwordx4 v[100:103], v4, s[48:49] offset:3072
	global_load_dwordx4 v[104:107], v213, s[48:49] offset:3072
	v_and_b32_e32 v212, 0xffffffc0, v165
	v_lshlrev_b32_e32 v212, 1, v212
	v_lshl_add_u32 v212, v152, 10, v212
	v_lshl_add_u32 v212, v166, 1, v212
	global_load_dwordx2 v[190:191], v212, s[50:51] offset:0
	global_load_dwordx2 v[192:193], v212, s[50:51] offset:16
	global_load_dwordx2 v[194:195], v212, s[50:51] offset:32
	global_load_dwordx2 v[198:199], v212, s[50:51] offset:48
	global_load_dwordx2 v[200:201], v212, s[50:51] offset:64
	global_load_dwordx2 v[202:203], v212, s[50:51] offset:80
	global_load_dwordx2 v[216:217], v212, s[50:51] offset:96
	global_load_dwordx2 v[248:249], v212, s[50:51] offset:112
	v_exp_f32_e32 v80, v80
	v_exp_f32_e32 v81, v81
	v_exp_f32_e32 v82, v82
	v_exp_f32_e32 v83, v83
	v_exp_f32_e32 v84, v84
	v_exp_f32_e32 v85, v85
	v_cvt_pk_bf16_f32 v6, v80, v81
	v_exp_f32_e32 v86, v86
	v_exp_f32_e32 v87, v87
	v_cvt_pk_bf16_f32 v7, v82, v83
	v_cvt_pk_bf16_f32 v8, v84, v85
	v_exp_f32_e32 v88, v88
	v_exp_f32_e32 v89, v89
	v_cvt_pk_bf16_f32 v9, v86, v87
	s_nop 1
	s_waitcnt lgkmcnt(6)
	v_mfma_f32_32x32x16_bf16 v[64:79], v[204:207], v[6:9], v[64:79]
	ds_read_b64_tr_b16 v[204:205], v155 offset:53248
	ds_read_b64_tr_b16 v[206:207], v171 offset:53248
	v_exp_f32_e32 v90, v90
	v_exp_f32_e32 v91, v91
	v_cvt_pk_bf16_f32 v10, v88, v89
	s_waitcnt lgkmcnt(6)
	v_mfma_f32_32x32x16_bf16 v[48:63], v[208:211], v[6:9], v[48:63]
	ds_read_b64_tr_b16 v[208:209], v168 offset:53248
	ds_read_b64_tr_b16 v[210:211], v172 offset:53248
	v_exp_f32_e32 v92, v92
	v_exp_f32_e32 v93, v93
	v_cvt_pk_bf16_f32 v11, v90, v91
	s_waitcnt lgkmcnt(6)
	v_mfma_f32_32x32x16_bf16 v[32:47], v[176:179], v[6:9], v[32:47]
	ds_read_b64_tr_b16 v[176:177], v169 offset:53248
	ds_read_b64_tr_b16 v[178:179], v173 offset:53248
	v_exp_f32_e32 v94, v94
	v_exp_f32_e32 v95, v95
	s_waitcnt lgkmcnt(6)
	v_mfma_f32_32x32x16_bf16 v[16:31], v[184:187], v[6:9], v[16:31]
	ds_read_b64_tr_b16 v[184:185], v170 offset:53248
	ds_read_b64_tr_b16 v[186:187], v174 offset:53248
	v_cvt_pk_bf16_f32 v12, v92, v93
	v_cvt_pk_bf16_f32 v13, v94, v95
	s_nop 1
	s_waitcnt lgkmcnt(6)
	v_mfma_f32_32x32x16_bf16 v[64:79], v[204:207], v[10:13], v[64:79]
	v_add_f32_e32 v175, v175, v80
	v_add_f32_e32 v175, v175, v81
	v_add_f32_e32 v175, v175, v82
	v_add_f32_e32 v175, v175, v83
	s_waitcnt lgkmcnt(4)
	v_mfma_f32_32x32x16_bf16 v[48:63], v[208:211], v[10:13], v[48:63]
	v_add_f32_e32 v175, v175, v84
	v_add_f32_e32 v175, v175, v85
	v_add_f32_e32 v175, v175, v86
	v_add_f32_e32 v175, v175, v87
	s_waitcnt lgkmcnt(2)
	v_mfma_f32_32x32x16_bf16 v[32:47], v[176:179], v[10:13], v[32:47]
	v_add_f32_e32 v175, v175, v88
	v_add_f32_e32 v175, v175, v89
	v_add_f32_e32 v175, v175, v90
	v_add_f32_e32 v175, v175, v91
	s_waitcnt lgkmcnt(0)
	v_mfma_f32_32x32x16_bf16 v[16:31], v[184:187], v[10:13], v[16:31]
	v_add_f32_e32 v175, v175, v92
	v_add_f32_e32 v175, v175, v93
	v_add_f32_e32 v175, v175, v94
	v_add_f32_e32 v175, v175, v95
	s_branch .Lat3_epi_b
.Lat3_smp_a:
	ds_read_b64_tr_b16 v[204:205], v155 offset:0
	ds_read_b64_tr_b16 v[206:207], v171 offset:0
	ds_read_b64_tr_b16 v[208:209], v168 offset:0
	ds_read_b64_tr_b16 v[210:211], v172 offset:0
	ds_read_b64_tr_b16 v[176:177], v169 offset:0
	ds_read_b64_tr_b16 v[178:179], v173 offset:0
	ds_read_b64_tr_b16 v[184:185], v170 offset:0
	ds_read_b64_tr_b16 v[186:187], v174 offset:0
	s_bfe_u32 s10, s83, 0x10001
	s_lshl_b32 s10, s10, 8
	s_addk_i32 s10, 0x3700
	s_and_saveexec_b64 s[18:19], s[80:81]
	s_cbranch_execz .Lat3_tk_sa
	v_mov_b32_e32 v2, s10
	v_mov_b32_e32 v3, 1
	global_atomic_add v215, v2, v3, s[78:79] sc0
.Lat3_tk_sa:
	s_or_b64 exec, exec, s[18:19]
	v_and_b32_e32 v3, 63, v165
	v_lshlrev_b32_e32 v3, 4, v3
	v_lshl_add_u32 v3, v154, 14, v3
	v_add_u32_e32 v4, 0x1000, v3
	v_add_u32_e32 v5, 0x2000, v3
	v_add_u32_e32 v213, 0x3000, v3
	global_load_dwordx4 v[148:151], v3, s[48:49] offset:0
	global_load_dwordx4 v[144:147], v5, s[48:49] offset:0
	global_load_dwordx4 v[140:143], v3, s[48:49] offset:1024
	global_load_dwordx4 v[136:139], v5, s[48:49] offset:1024
	global_load_dwordx4 v[132:135], v3, s[48:49] offset:2048
	global_load_dwordx4 v[128:131], v5, s[48:49] offset:2048
	global_load_dwordx4 v[124:127], v3, s[48:49] offset:3072
	global_load_dwordx4 v[120:123], v5, s[48:49] offset:3072
	global_load_dwordx4 v[116:119], v4, s[48:49] offset:0
	global_load_dwordx4 v[112:115], v213, s[48:49] offset:0
	global_load_dwordx4 v[220:223], v4, s[48:49] offset:1024
	global_load_dwordx4 v[224:227], v213, s[48:49] offset:1024
	global_load_dwordx4 v[228:231], v4, s[48:49] offset:2048
	global_load_dwordx4 v[80:83], v213, s[48:49] offset:2048
	global_load_dwordx4 v[84:87], v4, s[48:49] offset:3072
	global_load_dwordx4 v[88:91], v213, s[48:49] offset:3072
	v_and_b32_e32 v212, 0xffffffc0, v165
	v_lshlrev_b32_e32 v212, 1, v212
	v_lshl_add_u32 v212, v152, 10, v212
	v_lshl_add_u32 v212, v166, 1, v212
	global_load_dwordx2 v[190:191], v212, s[50:51] offset:0
	global_load_dwordx2 v[192:193], v212, s[50:51] offset:16
	global_load_dwordx2 v[194:195], v212, s[50:51] offset:32
	global_load_dwordx2 v[198:199], v212, s[50:51] offset:48
	global_load_dwordx2 v[200:201], v212, s[50:51] offset:64
	global_load_dwordx2 v[202:203], v212, s[50:51] offset:80
	global_load_dwordx2 v[216:217], v212, s[50:51] offset:96
	global_load_dwordx2 v[248:249], v212, s[50:51] offset:112
	v_exp_f32_e32 v96, v96
	v_exp_f32_e32 v97, v97
	v_exp_f32_e32 v98, v98
	v_exp_f32_e32 v99, v99
	v_exp_f32_e32 v100, v100
	v_exp_f32_e32 v101, v101
	v_cvt_pk_bf16_f32 v6, v96, v97
	v_exp_f32_e32 v102, v102
	v_exp_f32_e32 v103, v103
	v_cvt_pk_bf16_f32 v7, v98, v99
	v_cvt_pk_bf16_f32 v8, v100, v101
	v_exp_f32_e32 v104, v104
	v_exp_f32_e32 v105, v105
	v_cvt_pk_bf16_f32 v9, v102, v103
	s_nop 1
	s_waitcnt lgkmcnt(6)
	v_mfma_f32_32x32x16_bf16 v[64:79], v[204:207], v[6:9], v[64:79]
	ds_read_b64_tr_b16 v[204:205], v155 offset:4096
	ds_read_b64_tr_b16 v[206:207], v171 offset:4096
	v_exp_f32_e32 v106, v106
	v_exp_f32_e32 v107, v107
	v_cvt_pk_bf16_f32 v10, v104, v105
	s_waitcnt lgkmcnt(6)
	v_mfma_f32_32x32x16_bf16 v[48:63], v[208:211], v[6:9], v[48:63]
	ds_read_b64_tr_b16 v[208:209], v168 offset:4096
	ds_read_b64_tr_b16 v[210:211], v172 offset:4096
	v_exp_f32_e32 v108, v108
	v_exp_f32_e32 v109, v109
	v_cvt_pk_bf16_f32 v11, v106, v107
	s_waitcnt lgkmcnt(6)
	v_mfma_f32_32x32x16_bf16 v[32:47], v[176:179], v[6:9], v[32:47]
	ds_read_b64_tr_b16 v[176:177], v169 offset:4096
	ds_read_b64_tr_b16 v[178:179], v173 offset:4096
	v_exp_f32_e32 v110, v110
	v_exp_f32_e32 v111, v111
	s_waitcnt lgkmcnt(6)
	v_mfma_f32_32x32x16_bf16 v[16:31], v[184:187], v[6:9], v[16:31]
	ds_read_b64_tr_b16 v[184:185], v170 offset:4096
	ds_read_b64_tr_b16 v[186:187], v174 offset:4096
	v_cvt_pk_bf16_f32 v12, v108, v109
	v_cvt_pk_bf16_f32 v13, v110, v111
	s_nop 1
	s_waitcnt lgkmcnt(6)
	v_mfma_f32_32x32x16_bf16 v[64:79], v[204:207], v[10:13], v[64:79]
	v_add_f32_e32 v175, v175, v96
	v_add_f32_e32 v175, v175, v97
	v_add_f32_e32 v175, v175, v98
	v_add_f32_e32 v175, v175, v99
	s_waitcnt lgkmcnt(4)
	v_mfma_f32_32x32x16_bf16 v[48:63], v[208:211], v[10:13], v[48:63]
	v_add_f32_e32 v175, v175, v100
	v_add_f32_e32 v175, v175, v101
	v_add_f32_e32 v175, v175, v102
	v_add_f32_e32 v175, v175, v103
	s_waitcnt lgkmcnt(2)
	v_mfma_f32_32x32x16_bf16 v[32:47], v[176:179], v[10:13], v[32:47]
	v_add_f32_e32 v175, v175, v104
	v_add_f32_e32 v175, v175, v105
	v_add_f32_e32 v175, v175, v106
	v_add_f32_e32 v175, v175, v107
	s_waitcnt lgkmcnt(0)
	v_mfma_f32_32x32x16_bf16 v[16:31], v[184:187], v[10:13], v[16:31]
	v_add_f32_e32 v175, v175, v108
	v_add_f32_e32 v175, v175, v109
	v_add_f32_e32 v175, v175, v110
	v_add_f32_e32 v175, v175, v111
	s_branch .Lat3_epi_a
.Lat3_smp_b:
	ds_read_b64_tr_b16 v[204:205], v155 offset:20480
	ds_read_b64_tr_b16 v[206:207], v171 offset:20480
	ds_read_b64_tr_b16 v[208:209], v168 offset:20480
	ds_read_b64_tr_b16 v[210:211], v172 offset:20480
	ds_read_b64_tr_b16 v[176:177], v169 offset:20480
	ds_read_b64_tr_b16 v[178:179], v173 offset:20480
	ds_read_b64_tr_b16 v[184:185], v170 offset:20480
	ds_read_b64_tr_b16 v[186:187], v174 offset:20480
	s_bfe_u32 s10, s83, 0x10001
	s_lshl_b32 s10, s10, 8
	s_addk_i32 s10, 0x3700
	s_and_saveexec_b64 s[18:19], s[80:81]
	s_cbranch_execz .Lat3_tk_sb
	v_mov_b32_e32 v2, s10
	v_mov_b32_e32 v3, 1
	global_atomic_add v215, v2, v3, s[78:79] sc0
.Lat3_tk_sb:
	s_or_b64 exec, exec, s[18:19]
	v_and_b32_e32 v3, 63, v165
	v_lshlrev_b32_e32 v3, 4, v3
	v_lshl_add_u32 v3, v154, 14, v3
	v_add_u32_e32 v4, 0x1000, v3
	v_add_u32_e32 v5, 0x2000, v3
	v_add_u32_e32 v213, 0x3000, v3
	global_load_dwordx4 v[148:151], v3, s[48:49] offset:0
	global_load_dwordx4 v[144:147], v5, s[48:49] offset:0
	global_load_dwordx4 v[140:143], v3, s[48:49] offset:1024
	global_load_dwordx4 v[136:139], v5, s[48:49] offset:1024
	global_load_dwordx4 v[132:135], v3, s[48:49] offset:2048
	global_load_dwordx4 v[128:131], v5, s[48:49] offset:2048
	global_load_dwordx4 v[124:127], v3, s[48:49] offset:3072
	global_load_dwordx4 v[120:123], v5, s[48:49] offset:3072
	global_load_dwordx4 v[116:119], v4, s[48:49] offset:0
	global_load_dwordx4 v[112:115], v213, s[48:49] offset:0
	global_load_dwordx4 v[220:223], v4, s[48:49] offset:1024
	global_load_dwordx4 v[224:227], v213, s[48:49] offset:1024
	global_load_dwordx4 v[228:231], v4, s[48:49] offset:2048
	global_load_dwordx4 v[80:83], v213, s[48:49] offset:2048
	global_load_dwordx4 v[84:87], v4, s[48:49] offset:3072
	global_load_dwordx4 v[88:91], v213, s[48:49] offset:3072
	v_and_b32_e32 v212, 0xffffffc0, v165
	v_lshlrev_b32_e32 v212, 1, v212
	v_lshl_add_u32 v212, v152, 10, v212
	v_lshl_add_u32 v212, v166, 1, v212
	global_load_dwordx2 v[190:191], v212, s[50:51] offset:0
	global_load_dwordx2 v[192:193], v212, s[50:51] offset:16
	global_load_dwordx2 v[194:195], v212, s[50:51] offset:32
	global_load_dwordx2 v[198:199], v212, s[50:51] offset:48
	global_load_dwordx2 v[200:201], v212, s[50:51] offset:64
	global_load_dwordx2 v[202:203], v212, s[50:51] offset:80
	global_load_dwordx2 v[216:217], v212, s[50:51] offset:96
	global_load_dwordx2 v[248:249], v212, s[50:51] offset:112
	v_exp_f32_e32 v96, v96
	v_exp_f32_e32 v97, v97
	v_exp_f32_e32 v98, v98
	v_exp_f32_e32 v99, v99
	v_exp_f32_e32 v100, v100
	v_exp_f32_e32 v101, v101
	v_cvt_pk_bf16_f32 v6, v96, v97
	v_exp_f32_e32 v102, v102
	v_exp_f32_e32 v103, v103
	v_cvt_pk_bf16_f32 v7, v98, v99
	v_cvt_pk_bf16_f32 v8, v100, v101
	v_exp_f32_e32 v104, v104
	v_exp_f32_e32 v105, v105
	v_cvt_pk_bf16_f32 v9, v102, v103
	s_nop 1
	s_waitcnt lgkmcnt(6)
	v_mfma_f32_32x32x16_bf16 v[64:79], v[204:207], v[6:9], v[64:79]
	ds_read_b64_tr_b16 v[204:205], v155 offset:24576
	ds_read_b64_tr_b16 v[206:207], v171 offset:24576
	v_exp_f32_e32 v106, v106
	v_exp_f32_e32 v107, v107
	v_cvt_pk_bf16_f32 v10, v104, v105
	s_waitcnt lgkmcnt(6)
	v_mfma_f32_32x32x16_bf16 v[48:63], v[208:211], v[6:9], v[48:63]
	ds_read_b64_tr_b16 v[208:209], v168 offset:24576
	ds_read_b64_tr_b16 v[210:211], v172 offset:24576
	v_exp_f32_e32 v108, v108
	v_exp_f32_e32 v109, v109
	v_cvt_pk_bf16_f32 v11, v106, v107
	s_waitcnt lgkmcnt(6)
	v_mfma_f32_32x32x16_bf16 v[32:47], v[176:179], v[6:9], v[32:47]
	ds_read_b64_tr_b16 v[176:177], v169 offset:24576
	ds_read_b64_tr_b16 v[178:179], v173 offset:24576
	v_exp_f32_e32 v110, v110
	v_exp_f32_e32 v111, v111
	s_waitcnt lgkmcnt(6)
	v_mfma_f32_32x32x16_bf16 v[16:31], v[184:187], v[6:9], v[16:31]
	ds_read_b64_tr_b16 v[184:185], v170 offset:24576
	ds_read_b64_tr_b16 v[186:187], v174 offset:24576
	v_cvt_pk_bf16_f32 v12, v108, v109
	v_cvt_pk_bf16_f32 v13, v110, v111
	s_nop 1
	s_waitcnt lgkmcnt(6)
	v_mfma_f32_32x32x16_bf16 v[64:79], v[204:207], v[10:13], v[64:79]
	v_add_f32_e32 v175, v175, v96
	v_add_f32_e32 v175, v175, v97
	v_add_f32_e32 v175, v175, v98
	v_add_f32_e32 v175, v175, v99
	s_waitcnt lgkmcnt(4)
	v_mfma_f32_32x32x16_bf16 v[48:63], v[208:211], v[10:13], v[48:63]
	v_add_f32_e32 v175, v175, v100
	v_add_f32_e32 v175, v175, v101
	v_add_f32_e32 v175, v175, v102
	v_add_f32_e32 v175, v175, v103
	s_waitcnt lgkmcnt(2)
	v_mfma_f32_32x32x16_bf16 v[32:47], v[176:179], v[10:13], v[32:47]
	v_add_f32_e32 v175, v175, v104
	v_add_f32_e32 v175, v175, v105
	v_add_f32_e32 v175, v175, v106
	v_add_f32_e32 v175, v175, v107
	s_waitcnt lgkmcnt(0)
	v_mfma_f32_32x32x16_bf16 v[16:31], v[184:187], v[10:13], v[16:31]
	v_add_f32_e32 v175, v175, v108
	v_add_f32_e32 v175, v175, v109
	v_add_f32_e32 v175, v175, v110
	v_add_f32_e32 v175, v175, v111
	s_branch .Lat3_epi_a
.Lat3_smp_c:
	ds_read_b64_tr_b16 v[204:205], v155 offset:40960
	ds_read_b64_tr_b16 v[206:207], v171 offset:40960
	ds_read_b64_tr_b16 v[208:209], v168 offset:40960
	ds_read_b64_tr_b16 v[210:211], v172 offset:40960
	ds_read_b64_tr_b16 v[176:177], v169 offset:40960
	ds_read_b64_tr_b16 v[178:179], v173 offset:40960
	ds_read_b64_tr_b16 v[184:185], v170 offset:40960
	ds_read_b64_tr_b16 v[186:187], v174 offset:40960
	s_bfe_u32 s10, s83, 0x10001
	s_lshl_b32 s10, s10, 8
	s_addk_i32 s10, 0x3700
	s_and_saveexec_b64 s[18:19], s[80:81]
	s_cbranch_execz .Lat3_tk_sc
	v_mov_b32_e32 v2, s10
	v_mov_b32_e32 v3, 1
	global_atomic_add v215, v2, v3, s[78:79] sc0
.Lat3_tk_sc:
	s_or_b64 exec, exec, s[18:19]
	v_and_b32_e32 v3, 63, v165
	v_lshlrev_b32_e32 v3, 4, v3
	v_lshl_add_u32 v3, v154, 14, v3
	v_add_u32_e32 v4, 0x1000, v3
	v_add_u32_e32 v5, 0x2000, v3
	v_add_u32_e32 v213, 0x3000, v3
	global_load_dwordx4 v[148:151], v3, s[48:49] offset:0
	global_load_dwordx4 v[144:147], v5, s[48:49] offset:0
	global_load_dwordx4 v[140:143], v3, s[48:49] offset:1024
	global_load_dwordx4 v[136:139], v5, s[48:49] offset:1024
	global_load_dwordx4 v[132:135], v3, s[48:49] offset:2048
	global_load_dwordx4 v[128:131], v5, s[48:49] offset:2048
	global_load_dwordx4 v[124:127], v3, s[48:49] offset:3072
	global_load_dwordx4 v[120:123], v5, s[48:49] offset:3072
	global_load_dwordx4 v[116:119], v4, s[48:49] offset:0
	global_load_dwordx4 v[112:115], v213, s[48:49] offset:0
	global_load_dwordx4 v[220:223], v4, s[48:49] offset:1024
	global_load_dwordx4 v[224:227], v213, s[48:49] offset:1024
	global_load_dwordx4 v[228:231], v4, s[48:49] offset:2048
	global_load_dwordx4 v[80:83], v213, s[48:49] offset:2048
	global_load_dwordx4 v[84:87], v4, s[48:49] offset:3072
	global_load_dwordx4 v[88:91], v213, s[48:49] offset:3072
	v_and_b32_e32 v212, 0xffffffc0, v165
	v_lshlrev_b32_e32 v212, 1, v212
	v_lshl_add_u32 v212, v152, 10, v212
	v_lshl_add_u32 v212, v166, 1, v212
	global_load_dwordx2 v[190:191], v212, s[50:51] offset:0
	global_load_dwordx2 v[192:193], v212, s[50:51] offset:16
	global_load_dwordx2 v[194:195], v212, s[50:51] offset:32
	global_load_dwordx2 v[198:199], v212, s[50:51] offset:48
	global_load_dwordx2 v[200:201], v212, s[50:51] offset:64
	global_load_dwordx2 v[202:203], v212, s[50:51] offset:80
	global_load_dwordx2 v[216:217], v212, s[50:51] offset:96
	global_load_dwordx2 v[248:249], v212, s[50:51] offset:112
	v_exp_f32_e32 v96, v96
	v_exp_f32_e32 v97, v97
	v_exp_f32_e32 v98, v98
	v_exp_f32_e32 v99, v99
	v_exp_f32_e32 v100, v100
	v_exp_f32_e32 v101, v101
	v_cvt_pk_bf16_f32 v6, v96, v97
	v_exp_f32_e32 v102, v102
	v_exp_f32_e32 v103, v103
	v_cvt_pk_bf16_f32 v7, v98, v99
	v_cvt_pk_bf16_f32 v8, v100, v101
	v_exp_f32_e32 v104, v104
	v_exp_f32_e32 v105, v105
	v_cvt_pk_bf16_f32 v9, v102, v103
	s_nop 1
	s_waitcnt lgkmcnt(6)
	v_mfma_f32_32x32x16_bf16 v[64:79], v[204:207], v[6:9], v[64:79]
	ds_read_b64_tr_b16 v[204:205], v155 offset:45056
	ds_read_b64_tr_b16 v[206:207], v171 offset:45056
	v_exp_f32_e32 v106, v106
	v_exp_f32_e32 v107, v107
	v_cvt_pk_bf16_f32 v10, v104, v105
	s_waitcnt lgkmcnt(6)
	v_mfma_f32_32x32x16_bf16 v[48:63], v[208:211], v[6:9], v[48:63]
	ds_read_b64_tr_b16 v[208:209], v168 offset:45056
	ds_read_b64_tr_b16 v[210:211], v172 offset:45056
	v_exp_f32_e32 v108, v108
	v_exp_f32_e32 v109, v109
	v_cvt_pk_bf16_f32 v11, v106, v107
	s_waitcnt lgkmcnt(6)
	v_mfma_f32_32x32x16_bf16 v[32:47], v[176:179], v[6:9], v[32:47]
	ds_read_b64_tr_b16 v[176:177], v169 offset:45056
	ds_read_b64_tr_b16 v[178:179], v173 offset:45056
	v_exp_f32_e32 v110, v110
	v_exp_f32_e32 v111, v111
	s_waitcnt lgkmcnt(6)
	v_mfma_f32_32x32x16_bf16 v[16:31], v[184:187], v[6:9], v[16:31]
	ds_read_b64_tr_b16 v[184:185], v170 offset:45056
	ds_read_b64_tr_b16 v[186:187], v174 offset:45056
	v_cvt_pk_bf16_f32 v12, v108, v109
	v_cvt_pk_bf16_f32 v13, v110, v111
	s_nop 1
	s_waitcnt lgkmcnt(6)
	v_mfma_f32_32x32x16_bf16 v[64:79], v[204:207], v[10:13], v[64:79]
	v_add_f32_e32 v175, v175, v96
	v_add_f32_e32 v175, v175, v97
	v_add_f32_e32 v175, v175, v98
	v_add_f32_e32 v175, v175, v99
	s_waitcnt lgkmcnt(4)
	v_mfma_f32_32x32x16_bf16 v[48:63], v[208:211], v[10:13], v[48:63]
	v_add_f32_e32 v175, v175, v100
	v_add_f32_e32 v175, v175, v101
	v_add_f32_e32 v175, v175, v102
	v_add_f32_e32 v175, v175, v103
	s_waitcnt lgkmcnt(2)
	v_mfma_f32_32x32x16_bf16 v[32:47], v[176:179], v[10:13], v[32:47]
	v_add_f32_e32 v175, v175, v104
	v_add_f32_e32 v175, v175, v105
	v_add_f32_e32 v175, v175, v106
	v_add_f32_e32 v175, v175, v107
	s_waitcnt lgkmcnt(0)
	v_mfma_f32_32x32x16_bf16 v[16:31], v[184:187], v[10:13], v[16:31]
	v_add_f32_e32 v175, v175, v108
	v_add_f32_e32 v175, v175, v109
	v_add_f32_e32 v175, v175, v110
	v_add_f32_e32 v175, v175, v111
	s_branch .Lat3_epi_a
